# combined: column masks precombined per task, row-phase x loads hoisted, scan state-update LDS reads batched, GEMM loop at offset 24 (checking steady-state effect; single-run timing is placement-noisy)
# speedup vs baseline: 1.0048x; 1.0048x over previous
; #define LAS __attribute__((address_space(3)))
; __device__ __forceinline__ void scan_phase(const Args& a, LAS unsigned char* lds, int G) {
;     ...
;             LAS unsigned char* B = lds + (ci & 1) * SC_BUF;
;             bf16x8 vf_next = vfn;
;             if (ci + 1 < 72) { SCAN_PREP(lds + ((ci + 1) & 1) * SC_BUF); }
;             if (ci + 2 < 72) { SCAN_RAW(ci + 2); }
;             int t0; scan_chunk_t0(ci, b, dir, t0);
;             bf16x8 vcur = vf;
;             if (dir) { bf16x8 t = vf; vcur[0] = t[7]; vcur[1] = t[6]; vcur[2] = t[5]; vcur[3] = t[4]; vcur[4] = t[3]; vcur[5] = t[2]; vcur[6] = t[1]; vcur[7] = t[0]; }
;             bf16x8 qb[2][4];
; #pragma unroll
;             for (int tb = 0; tb < 2; ++tb)
; #pragma unroll
;                 for (int c = 0; c < 4; ++c) qb[tb][c] = *(const LAS bf16x8*)(B + SC_QT + ((16 * tb + fr) * 136 + 32 * c + 8 * fq) * 2);
;             f32x4 att[2][2];
; #pragma unroll
;             for (int sb = 0; sb < 2; ++sb) {
;                 att[sb][0] = (f32x4){0.f, 0.f, 0.f, 0.f}; att[sb][1] = (f32x4){0.f, 0.f, 0.f, 0.f};
;                 const int srow = 8 * (fr >> 2) + 4 * sb + (fr & 3);
; #pragma unroll
;                 for (int c = 0; c < 4; ++c) {
;                     const bf16x8 ka = *(const LAS bf16x8*)(B + SC_KT + (srow * 136 + 32 * c + 8 * fq) * 2);
;                     att[sb][0] = __builtin_amdgcn_mfma_f32_16x16x32_bf16(ka, qb[0][c], att[sb][0], 0, 0, 0);
;                     att[sb][1] = __builtin_amdgcn_mfma_f32_16x16x32_bf16(ka, qb[1][c], att[sb][1], 0, 0, 0);
;                 }
;             }
;             f32x4 OT[2];
; #pragma unroll
;             for (int tb = 0; tb < 2; ++tb) {
;                 const int t = 16 * tb + fr;
; #pragma unroll
;                 for (int sb = 0; sb < 2; ++sb)
; #pragma unroll
;                     for (int i = 0; i < 4; ++i) { const int sa = 8 * fq + 4 * sb + i; att[sb][tb][i] = (sa <= t) ? att[sb][tb][i] : 0.f; }
;                 union { u32x4 u; bf16x8 v; } P; P.u.x = pk2(att[0][tb][0], att[0][tb][1]); P.u.y = pk2(att[0][tb][2], att[0][tb][3]); P.u.z = pk2(att[1][tb][0], att[1][tb][1]); P.u.w = pk2(att[1][tb][2], att[1][tb][3]);
;                 OT[tb] = __builtin_amdgcn_mfma_f32_16x16x32_bf16(vcur, P.v, (f32x4){0.f, 0.f, 0.f, 0.f}, 0, 0, 0);
;             }
; #pragma unroll
;             for (int c = 0; c < 4; ++c) {
.LBB0_93:
	s_bitcmp1_b32 s15, 0
	s_cselect_b32 s13, 0x6e00, 0
	s_add_i32 s23, s13, 0
	v_add_u32_e32 v166, s23, v107
	v_add_u32_e32 v60, v166, v127
	v_add_u32_e32 v167, v166, v129
	ds_read_b128 v[48:51], v60
	ds_read_b128 v[52:55], v60 offset:64
	ds_read_b128 v[56:59], v60 offset:128
	ds_read_b128 v[44:47], v60 offset:192
	ds_read_b128 v[72:75], v60 offset:4352
	ds_read_b128 v[80:83], v60 offset:4416
	ds_read_b128 v[76:79], v60 offset:4480
	ds_read_b128 v[68:71], v60 offset:4544
	ds_read_b128 v[60:63], v167 offset:8704
	ds_read_b128 v[150:153], v167 offset:8768
	v_alignbit_b32 v162, v39, v39, 16
	v_alignbit_b32 v163, v38, v38, 16
	v_alignbit_b32 v164, v37, v37, 16
	v_alignbit_b32 v165, v36, v36, 16
	v_cndmask_b32_e64 v39, v165, v39, s[78:79]
	s_waitcnt lgkmcnt(1)
	v_mfma_f32_16x16x32_bf16 v[64:67], v[60:63], v[48:51], 0
	v_cndmask_b32_e64 v38, v164, v38, s[78:79]
	ds_read_b128 v[158:161], v167 offset:9856
	v_cndmask_b32_e64 v37, v163, v37, s[78:79]
	v_mfma_f32_16x16x32_bf16 v[60:63], v[60:63], v[72:75], 0
	v_cndmask_b32_e64 v36, v162, v36, s[78:79]
	v_add_u32_e32 v162, v166, v130
	v_add_u32_e32 v163, s23, v131
	s_waitcnt lgkmcnt(1)
	v_mfma_f32_16x16x32_bf16 v[64:67], v[150:153], v[52:55], v[64:67]
	s_lshl_b32 s15, s91, 5
	s_add_i32 s15, s15, s12
	s_add_i32 s12, s15, 31
	v_mfma_f32_16x16x32_bf16 v[60:63], v[150:153], v[80:83], v[60:63]
	ds_read_b128 v[150:153], v167 offset:8832
	s_add_i32 s89, s89, -1
	s_add_i32 s90, s90, 1
	s_waitcnt lgkmcnt(0)
	v_mfma_f32_16x16x32_bf16 v[64:67], v[150:153], v[56:59], v[64:67]
	s_cmp_eq_u32 s90, 63
	v_mfma_f32_16x16x32_bf16 v[60:63], v[150:153], v[76:79], v[60:63]
	ds_read_b128 v[150:153], v167 offset:8896
	s_waitcnt lgkmcnt(0)
	v_mfma_f32_16x16x32_bf16 v[64:67], v[150:153], v[44:47], v[64:67]
	v_mfma_f32_16x16x32_bf16 v[150:153], v[150:153], v[68:71], v[60:63]
	s_nop 3
	ds_read_b128 v[60:63], v167 offset:9792
	s_waitcnt lgkmcnt(0)
	v_mfma_f32_16x16x32_bf16 v[154:157], v[60:63], v[48:51], 0
	v_mfma_f32_16x16x32_bf16 v[60:63], v[60:63], v[72:75], 0
	v_mfma_f32_16x16x32_bf16 v[154:157], v[158:161], v[52:55], v[154:157]
	v_mfma_f32_16x16x32_bf16 v[60:63], v[158:161], v[80:83], v[60:63]
	ds_read_b128 v[158:161], v167 offset:9920
	s_waitcnt lgkmcnt(0)
	v_mfma_f32_16x16x32_bf16 v[154:157], v[158:161], v[56:59], v[154:157]
	v_mfma_f32_16x16x32_bf16 v[60:63], v[158:161], v[76:79], v[60:63]
	ds_read_b128 v[158:161], v167 offset:9984
	s_waitcnt lgkmcnt(0)
	v_mfma_f32_16x16x32_bf16 v[154:157], v[158:161], v[44:47], v[154:157]
	v_mfma_f32_16x16x32_bf16 v[158:161], v[158:161], v[68:71], v[60:63]
	s_nop 3
	v_cvt_pk_bf16_f32 v60, v64, s0
	v_cvt_pk_bf16_f32 v61, v65, s0
	v_cndmask_b32_e64 v60, v60, 0, s[46:47]
	v_cndmask_b32_e64 v61, 0, v61, s[48:49]
	v_perm_b32 v60, v61, v60, s3
	v_cvt_pk_bf16_f32 v61, v66, s0
	v_cvt_pk_bf16_f32 v62, v67, s0
	v_cndmask_b32_e64 v61, v61, 0, s[50:51]
	v_cndmask_b32_e64 v62, v62, 0, s[52:53]
	v_perm_b32 v61, v62, v61, s3
	v_cvt_pk_bf16_f32 v62, v154, s0
	v_cvt_pk_bf16_f32 v63, v155, s0
	v_cndmask_b32_e64 v62, v62, 0, s[54:55]
	v_cndmask_b32_e64 v63, v63, 0, s[56:57]
	v_perm_b32 v62, v63, v62, s3
	v_cvt_pk_bf16_f32 v63, v156, s0
	v_cvt_pk_bf16_f32 v64, v157, s0
	v_cndmask_b32_e64 v63, v63, 0, s[58:59]
	v_cndmask_b32_e64 v64, v64, 0, s[60:61]
	v_perm_b32 v63, v64, v63, s3
	v_cvt_pk_bf16_f32 v64, v150, s0
	v_cvt_pk_bf16_f32 v65, v151, s0
	v_cndmask_b32_e64 v64, v64, 0, s[62:63]
	v_cndmask_b32_e64 v65, 0, v65, s[64:65]
	v_perm_b32 v64, v65, v64, s3
	v_cvt_pk_bf16_f32 v65, v152, s0
	v_cvt_pk_bf16_f32 v66, v153, s0
	v_cndmask_b32_e64 v65, v65, 0, s[66:67]
	v_cndmask_b32_e64 v66, v66, 0, s[68:69]
	v_perm_b32 v65, v66, v65, s3
	v_cvt_pk_bf16_f32 v66, v158, s0
	v_cvt_pk_bf16_f32 v67, v159, s0
	v_cndmask_b32_e64 v66, v66, 0, s[70:71]
	v_cndmask_b32_e64 v67, v67, 0, s[72:73]
	v_perm_b32 v66, v67, v66, s3
	v_cvt_pk_bf16_f32 v67, v160, s0
	v_cvt_pk_bf16_f32 v150, v161, s0
	v_cndmask_b32_e64 v67, v67, 0, s[74:75]
	v_cndmask_b32_e64 v150, v150, 0, s[76:77]
	v_perm_b32 v67, v150, v67, s3
	v_mfma_f32_16x16x32_bf16 v[60:63], v[36:39], v[60:63], 0
	s_nop 0
	v_mfma_f32_16x16x32_bf16 v[150:153], v[36:39], v[64:67], 0
	v_cvt_pk_bf16_f32 v64, v0, v1
	v_cvt_pk_bf16_f32 v65, v2, v3
	v_cvt_pk_bf16_f32 v66, v24, v25
	v_cvt_pk_bf16_f32 v67, v26, v27
	s_nop 1
	v_mfma_f32_16x16x32_bf16 v[150:153], v[64:67], v[72:75], v[150:153]
	v_cvt_pk_bf16_f32 v72, v12, v13
	v_cvt_pk_bf16_f32 v73, v14, v15
	v_cvt_pk_bf16_f32 v74, v20, v21
	v_cvt_pk_bf16_f32 v75, v22, v23
	s_nop 1
	v_mfma_f32_16x16x32_bf16 v[150:153], v[72:75], v[80:83], v[150:153]
	v_cvt_pk_bf16_f32 v80, v8, v9
	v_cvt_pk_bf16_f32 v81, v10, v11
	v_cvt_pk_bf16_f32 v82, v16, v17
	v_cvt_pk_bf16_f32 v83, v18, v19
	s_nop 1
	v_mfma_f32_16x16x32_bf16 v[150:153], v[80:83], v[76:79], v[150:153]
	v_cvt_pk_bf16_f32 v76, v4, v5
	v_cvt_pk_bf16_f32 v77, v6, v7
	v_cvt_pk_bf16_f32 v78, v28, v29
	v_cvt_pk_bf16_f32 v79, v30, v31
	s_nop 1
	v_mfma_f32_16x16x32_bf16 v[68:71], v[76:79], v[68:71], v[150:153]
	s_nop 2
	ds_read_b128 v[168:171], v162 offset:17408
	ds_read_b128 v[172:175], v162 offset:17728
	ds_read_b128 v[176:179], v162 offset:19968
	ds_read_b128 v[180:183], v162 offset:20288
	ds_read_b128 v[188:191], v162 offset:22528
	ds_read_b128 v[198:201], v162 offset:22848
	ds_read_b128 v[204:207], v162 offset:25088
	ds_read_b128 v[228:231], v163 offset:27648
	ds_read_b128 v[232:235], v163 offset:27664
	ds_read_b128 v[236:239], v163 offset:27776
	ds_read_b128 v[240:243], v163 offset:27792
	ds_read_b128 v[244:247], v163 offset:27904
	ds_read_b128 v[154:157], v163 offset:27920
	ds_read_b128 v[158:161], v163 offset:28032
	ds_read_b128 v[150:153], v163 offset:28048
	s_waitcnt lgkmcnt(7)
; #define LAS __attribute__((address_space(3)))
; #define SCAN_BAR() do { asm volatile("s_waitcnt lgkmcnt(0)" ::: "memory"); __builtin_amdgcn_s_barrier(); asm volatile("" ::: "memory"); } while (0)
; __device__ __forceinline__ void scan_phase(const Args& a, LAS unsigned char* lds, int G) {
;     ...
; #pragma unroll
;             for (int kb = 0; kb < 8; ++kb) {
;                 const int krow = 32 * (kb >> 1) + 8 * (fr >> 2) + 4 * (kb & 1) + (fr & 3);
;                 const bf16x8 ka = *(const LAS bf16x8*)(B + SC_KH + krow * 80 + fq * 16);
;                 const f32x4 dc = *(const LAS f32x4*)(B + SC_DEC + (32 * (kb >> 1) + 8 * fq + 4 * (kb & 1)) * 4);
;                 S[kb] = __builtin_amdgcn_mfma_f32_16x16x32_bf16(ka, vcur, S[kb] * dc, 0, 0, 0);
;             }
; #pragma unroll
;             for (int tb = 0; tb < 2; ++tb) {
;                 const int tau = 16 * tb + fr; const int tok = dir ? t0 + 31 - tau : t0 + tau;
;                 u32x2 w; w.x = pk2(OT[tb][0], OT[tb][1]); w.y = pk2(OT[tb][2], OT[tb][3]);
;                 *(u32x2*)(O + (size_t)tok * DI + h * 128 + 16 * wave + 4 * fq) = w;
;             }
;             vf = vf_next;
;             SCAN_BAR();
;         }
	v_pk_mul_f32 v[2:3], v[2:3], v[230:231]
	v_pk_mul_f32 v[0:1], v[0:1], v[228:229]
	ds_read_b128 v[228:231], v162 offset:25408
	s_waitcnt lgkmcnt(7)
	v_pk_mul_f32 v[26:27], v[26:27], v[234:235]
	v_pk_mul_f32 v[24:25], v[24:25], v[232:233]
	v_mfma_f32_16x16x32_bf16 v[0:3], v[168:171], v[36:39], v[0:3]
	s_waitcnt lgkmcnt(6)
	v_pk_mul_f32 v[14:15], v[14:15], v[238:239]
	v_pk_mul_f32 v[12:13], v[12:13], v[236:237]
	v_mfma_f32_16x16x32_bf16 v[24:27], v[172:175], v[36:39], v[24:27]
	s_waitcnt lgkmcnt(5)
	v_pk_mul_f32 v[22:23], v[22:23], v[242:243]
	v_pk_mul_f32 v[20:21], v[20:21], v[240:241]
	v_mfma_f32_16x16x32_bf16 v[12:15], v[176:179], v[36:39], v[12:15]
	s_waitcnt lgkmcnt(4)
	v_pk_mul_f32 v[10:11], v[10:11], v[246:247]
	v_pk_mul_f32 v[8:9], v[8:9], v[244:245]
	v_mfma_f32_16x16x32_bf16 v[20:23], v[180:183], v[36:39], v[20:23]
	s_waitcnt lgkmcnt(3)
	v_pk_mul_f32 v[18:19], v[18:19], v[156:157]
	v_pk_mul_f32 v[16:17], v[16:17], v[154:155]
	v_mfma_f32_16x16x32_bf16 v[8:11], v[188:191], v[36:39], v[8:11]
	s_waitcnt lgkmcnt(2)
	v_pk_mul_f32 v[6:7], v[6:7], v[160:161]
	v_pk_mul_f32 v[4:5], v[4:5], v[158:159]
	v_mfma_f32_16x16x32_bf16 v[16:19], v[198:201], v[36:39], v[16:19]
	s_waitcnt lgkmcnt(1)
	v_pk_mul_f32 v[30:31], v[30:31], v[152:153]
	v_pk_mul_f32 v[28:29], v[28:29], v[150:151]
	v_mfma_f32_16x16x32_bf16 v[4:7], v[204:207], v[36:39], v[4:7]
	s_waitcnt lgkmcnt(0)
	s_nop 0
	v_mfma_f32_16x16x32_bf16 v[28:31], v[228:231], v[36:39], v[28:31]
	v_mfma_f32_16x16x32_bf16 v[36:39], v[64:67], v[48:51], v[60:63]
	v_mfma_f32_16x16x32_bf16 v[36:39], v[72:75], v[52:55], v[36:39]
	v_mfma_f32_16x16x32_bf16 v[36:39], v[80:83], v[56:59], v[36:39]
	v_mfma_f32_16x16x32_bf16 v[36:39], v[76:79], v[44:47], v[36:39]
	v_sub_u32_e32 v44, s12, v85
	v_add_u32_e32 v45, s15, v85
	v_cndmask_b32_e64 v44, v44, v45, s[78:79]
	v_ashrrev_i32_e32 v45, 31, v44
	s_nop 3
	v_cvt_pk_bf16_f32 v36, v36, v37
	v_cvt_pk_bf16_f32 v37, v38, v39
	v_lshlrev_b64 v[38:39], 13, v[44:45]
	v_lshl_add_u64 v[38:39], v[94:95], 0, v[38:39]
	global_store_dwordx2 v[38:39], v[36:37], off
	v_sub_u32_e32 v36, s12, v128
	v_add_u32_e32 v37, s15, v128
	v_cndmask_b32_e64 v36, v36, v37, s[78:79]
	v_ashrrev_i32_e32 v37, 31, v36
	v_lshlrev_b64 v[36:37], 13, v[36:37]
	v_cvt_pk_bf16_f32 v38, v68, v69
	v_cvt_pk_bf16_f32 v39, v70, v71
	v_lshl_add_u64 v[36:37], v[94:95], 0, v[36:37]
	global_store_dwordx2 v[36:37], v[38:39], off
	s_waitcnt lgkmcnt(0)
	s_barrier
	s_cbranch_scc1 .LBB0_83
	v_mov_b64_e32 v[38:39], v[34:35]
	v_mov_b64_e32 v[36:37], v[32:33]
	s_branch .LBB0_87

; __device__ __forceinline__ void attn_phase(const Args& a, int layer, LAS unsigned char* lds, int G, int need_ctx) {
;     ...
;         const int r0a = min(max(r - 4, 0), 24), r0b = min(max(r - 3, 0), 24), nband = lat ? (r0b + 8 - r0a) : 0;
;         const int qr = r + (q >> 4), myr0 = (q >> 4) ? r0b : r0a;
;         const int cw = min(max(16 * j - 8, 0), 32), qcol = 16 * j + (q & 15), c0 = min(max(qcol - 8, 0), 48);
;         const int nst = nband + 8;
;         const int kb_lat = b * SEQ + r0a * 64 + cw, kb_ctx = MLAT + b * CTX;
;         const bf16_t* kbase = Kp + (size_t)h * 1024 + (size_t)(sig >> 3) * 32768 + (sig & 7) * 16 + 8 * hh;
;         const bf16_t* vbase = Vt + (size_t)h * 1024 + (size_t)hh * 32768 + q * 8;
;         float m_run = -1e30f, l_run = 0.f;
;         f32x16 OT[4];
; #pragma unroll
;         for (int d = 0; d < 4; ++d)
; #pragma unroll
;             for (int t = 0; t < 16; ++t) OT[d][t] = 0.f;
.LBB0_152:
	v_sub_u32_e64 v0, s6, 4 clamp
	v_mov_b32_e32 v15, 0
	v_readfirstlane_b32 s4, v0
	v_sub_u32_e64 v0, s6, 3 clamp
	s_min_u32 s37, s4, 24
	v_readfirstlane_b32 s4, v0
	s_min_u32 s4, s4, 24
	s_sub_i32 s5, s4, s37
	s_add_i32 s5, s5, 8
	s_andn2_b32 s100, s6, 2
	s_sub_i32 s100, s100, 4
	s_max_i32 s100, s100, 0
	s_min_i32 s100, s100, 24
	s_mov_b32 vcc_lo, s37
	s_mov_b32 s37, s100
	s_sub_i32 s100, vcc_lo, s100
	s_and_b64 s[0:1], s[0:1], exec
	s_cselect_b32 s15, s5, 0
	s_cmp_lt_i32 s15, -7
	v_mov_b32_e32 v14, v15
	v_mov_b32_e32 v13, v15
	v_mov_b32_e32 v12, v15
	v_mov_b32_e32 v11, v15
	v_mov_b32_e32 v10, v15
	v_mov_b32_e32 v9, v15
	v_mov_b32_e32 v8, v15
	v_mov_b32_e32 v7, v15
	v_mov_b32_e32 v6, v15
	v_mov_b32_e32 v5, v15
	v_mov_b32_e32 v4, v15
	v_mov_b32_e32 v3, v15
	v_mov_b32_e32 v2, v15
	v_mov_b32_e32 v1, v15
	v_mov_b32_e32 v0, v15
	v_mov_b32_e32 v31, v15
	v_mov_b32_e32 v30, v15
	v_mov_b32_e32 v29, v15
	v_mov_b32_e32 v28, v15
	v_mov_b32_e32 v27, v15
	v_mov_b32_e32 v26, v15
	v_mov_b32_e32 v25, v15
	v_mov_b32_e32 v24, v15
	v_mov_b32_e32 v23, v15
	v_mov_b32_e32 v22, v15
	v_mov_b32_e32 v21, v15
	v_mov_b32_e32 v20, v15
	v_mov_b32_e32 v19, v15
	v_mov_b32_e32 v18, v15
	v_mov_b32_e32 v17, v15
	v_mov_b32_e32 v16, v15
	v_mov_b32_e32 v47, v15
	v_mov_b32_e32 v46, v15
	v_mov_b32_e32 v45, v15
	v_mov_b32_e32 v44, v15
	v_mov_b32_e32 v43, v15
	v_mov_b32_e32 v42, v15
	v_mov_b32_e32 v41, v15
	v_mov_b32_e32 v40, v15
	v_mov_b32_e32 v39, v15
	v_mov_b32_e32 v38, v15
	v_mov_b32_e32 v37, v15
	v_mov_b32_e32 v36, v15
	v_mov_b32_e32 v35, v15
	v_mov_b32_e32 v34, v15
	v_mov_b32_e32 v33, v15
	v_mov_b32_e32 v32, v15
	v_mov_b32_e32 v63, v15
	v_mov_b32_e32 v62, v15
	v_mov_b32_e32 v61, v15
	v_mov_b32_e32 v60, v15
	v_mov_b32_e32 v59, v15
	v_mov_b32_e32 v58, v15
	v_mov_b32_e32 v57, v15
	v_mov_b32_e32 v56, v15
	v_mov_b32_e32 v55, v15
	v_mov_b32_e32 v54, v15
	v_mov_b32_e32 v53, v15
	v_mov_b32_e32 v52, v15
	v_mov_b32_e32 v51, v15
	v_mov_b32_e32 v50, v15
	v_mov_b32_e32 v49, v15
	v_mov_b32_e32 v48, v15
	v_mov_b32_e32 v64, v15
	s_cbranch_scc1 .LBB0_199
; __device__ __forceinline__ void attn_phase(const Args& a, int layer, LAS unsigned char* lds, int G, int need_ctx) {
;     ...
;         const int cw = min(max(16 * j - 8, 0), 32), qcol = 16 * j + (q & 15), c0 = min(max(qcol - 8, 0), 48);
;         const int nst = nband + 8;
;         const int kb_lat = b * SEQ + r0a * 64 + cw, kb_ctx = MLAT + b * CTX;
;         const bf16_t* kbase = Kp + (size_t)h * 1024 + (size_t)(sig >> 3) * 32768 + (sig & 7) * 16 + 8 * hh;
;         const bf16_t* vbase = Vt + (size_t)h * 1024 + (size_t)hh * 32768 + q * 8;
;         float m_run = -1e30f, l_run = 0.f;
;         f32x16 OT[4];
; #pragma unroll
;         for (int d = 0; d < 4; ++d)
; #pragma unroll
;             for (int t = 0; t < 16; ++t) OT[d][t] = 0.f;
;         bf16x8 kreg[8], vreg[8];
;         { const int kb0 = nband ? kb_lat : kb_ctx;
; #pragma unroll
;           for (int c = 0; c < 8; ++c) kreg[c] = *(const bf16x8*)(kbase + (size_t)(kb0 >> 3) * 32768 + 128 * c); }
;         for (int st = 0; st < nst; ++st) {
;             const bool isl = st < nband;
;             const int keybase = isl ? kb_lat + st * 64 : kb_ctx + 32 * (st - nband);
; #pragma unroll
;             for (int d = 0; d < 4; ++d)
; #pragma unroll
;                 for (int s2 = 0; s2 < 2; ++s2) vreg[d * 2 + s2] = *(const bf16x8*)(vbase + (size_t)(keybase >> 3) * 32768 + s2 * 65536 + d * 256);
;             f32x16 sc;
; #pragma unroll
;             for (int t = 0; t < 16; ++t) sc[t] = 0.f;
; #pragma unroll
;             for (int c = 0; c < 8; ++c) sc = __builtin_amdgcn_mfma_f32_32x32x16_bf16(kreg[c], qf[c], sc, 0, 0, 0);
;             if (st + 1 < nst) {
;                 const int kn = (st + 1 < nband) ? kb_lat + (st + 1) * 64 : kb_ctx + 32 * (st + 1 - nband);
; #pragma unroll
;                 for (int c = 0; c < 8; ++c) kreg[c] = *(const bf16x8*)(kbase + (size_t)(kn >> 3) * 32768 + 128 * c);
;             }
;             if (isl) {
;                 const int kr = r0a + st; const bool rowok = (kr >= myr0) && (kr < myr0 + 8);
;                 const int brow = (kr - qr + 7) * 31 - qcol + 15;
; #pragma unroll
;                 for (int t = 0; t < 16; ++t) {
;                     const int kc = cw + 16 * (t >> 3) + 8 * hh + (t & 7); const bool valid = rowok && (kc >= c0) && (kc < c0 + 16);
	v_sub_u32_e64 v0, s7, 8 clamp
	s_lshl_b32 s0, s23, 11
	s_lshl_b32 s1, s37, 6
	v_readfirstlane_b32 s5, v0
	s_or_b32 s0, s1, s0
	s_lshl_b32 s1, s23, 8
	s_min_u32 s12, s5, 32
	s_or_b32 s24, s0, s12
	s_add_i32 s13, s1, 0x2000
	v_readlane_b32 s0, v250, 8
	v_mov_b32_e32 v0, s4
	s_add_i32 s1, s37, s100
	v_mov_b32_e32 v2, s1
	v_readlane_b32 s1, v250, 9
	s_lshl_b32 s94, s36, 11
	s_add_i32 s25, s15, 8
	v_cndmask_b32_e64 v96, v0, v2, s[0:1]
	s_mov_b32 s1, s95
	v_writelane_b32 v250, s0, 12
	s_cmp_eq_u32 s15, 0
	v_or_b32_e32 v1, s7, v230
	v_writelane_b32 v250, s1, 13
	s_cselect_b32 s0, s13, s24
	s_cmp_lg_u32 s100, 0
	s_cselect_b32 s0, s13, s0
	s_ashr_i32 s0, s0, 3
	v_max_i32_e32 v0, 8, v1
	s_ashr_i32 s1, s0, 31
	v_lshl_add_u64 v[206:207], v[198:199], 0, s[94:95]
	v_add_u32_e32 v0, -8, v0
	s_lshl_b64 s[0:1], s[0:1], 16
	v_min_u32_e32 v2, 48, v0
	v_lshl_add_u64 v[0:1], v[206:207], 0, s[0:1]
	global_load_dwordx4 v[130:133], v[0:1], off offset:1792
	global_load_dwordx4 v[134:137], v[0:1], off offset:1536
	global_load_dwordx4 v[138:141], v[0:1], off offset:1280
	global_load_dwordx4 v[142:145], v[0:1], off offset:1024
	global_load_dwordx4 v[158:161], v[0:1], off offset:768
	global_load_dwordx4 v[154:157], v[0:1], off offset:512
	global_load_dwordx4 v[150:153], v[0:1], off offset:256
	global_load_dwordx4 v[146:149], v[0:1], off
	v_xor_b32_e32 v3, 32, v210
	v_cmp_lt_i32_e32 vcc, v3, v212
	v_add_u32_e32 v0, s12, v196
	v_add_u32_e32 v1, 16, v2
	v_cndmask_b32_e32 v3, v210, v3, vcc
	v_lshlrev_b32_e32 v235, 2, v3
	v_or_b32_e32 v3, 1, v0
	v_cmp_ge_u32_e64 s[40:41], v3, v2
	v_cmp_lt_u32_e64 s[42:43], v3, v1
	v_or_b32_e32 v3, 2, v0
	v_cmp_ge_u32_e64 s[44:45], v3, v2
	v_cmp_lt_u32_e64 s[46:47], v3, v1
	v_or_b32_e32 v3, 3, v0
	v_cmp_ge_u32_e64 s[48:49], v3, v2
	v_cmp_lt_u32_e64 s[50:51], v3, v1
	v_or_b32_e32 v3, 4, v0
	v_cmp_ge_u32_e64 s[52:53], v3, v2
	v_cmp_lt_u32_e64 s[54:55], v3, v1
	v_or_b32_e32 v3, 5, v0
	v_cmp_ge_u32_e64 s[56:57], v3, v2
	v_cmp_lt_u32_e64 s[58:59], v3, v1
	v_or_b32_e32 v3, 6, v0
	v_cmp_ge_u32_e64 s[60:61], v3, v2
	v_cmp_lt_u32_e64 s[62:63], v3, v1
	v_or_b32_e32 v3, 7, v0
	v_cmp_ge_u32_e64 s[64:65], v3, v2
	v_cmp_lt_u32_e64 s[66:67], v3, v1
	v_add_u32_e32 v3, 16, v0
	v_cmp_ge_u32_e64 s[68:69], v3, v2
	v_add_u32_e32 v3, 17, v0
	v_cmp_ge_u32_e64 s[72:73], v3, v2
	v_cmp_lt_u32_e64 s[74:75], v3, v1
	v_add_u32_e32 v3, 18, v0
	v_cmp_ge_u32_e64 s[76:77], v3, v2
	v_cmp_lt_u32_e64 s[78:79], v3, v1
	v_add_u32_e32 v3, 19, v0
	v_cmp_ge_u32_e64 s[82:83], v3, v2
	v_cmp_lt_u32_e64 s[84:85], v3, v1
	v_add_u32_e32 v3, 20, v0
	v_cmp_ge_u32_e64 s[86:87], v3, v2
	v_cmp_lt_u32_e64 s[88:89], v3, v1
	v_add_u32_e32 v3, 21, v0
	v_cmp_ge_u32_e64 s[0:1], v0, v2
	v_cmp_lt_u32_e64 s[38:39], v0, v1
	v_cmp_lt_u32_e64 s[70:71], v0, v2
	v_cmp_ge_u32_e64 s[90:91], v3, v2
	v_cmp_lt_u32_e64 s[92:93], v3, v1
	v_add_u32_e32 v3, 22, v0
	v_add_u32_e32 v0, 23, v0
	v_cmp_lt_u32_e64 s[96:97], v3, v1
	v_cmp_ge_u32_e64 s[98:99], v0, v2
	v_cmp_lt_u32_e64 s[4:5], v0, v1
	s_mul_i32 s23, s37, 31
	v_add_u32_e32 v0, s7, v230
	v_add_u32_e32 v1, s6, v229
	v_sub_u32_e32 v0, s23, v0
	v_mul_u32_u24_e32 v1, 31, v1
	v_sub_u32_e32 v0, v0, v1
	s_lshl_b32 s12, s12, 2
	v_lshlrev_b32_e32 v0, 2, v0
	s_lshl_b32 s6, s15, 5
	v_mov_b32_e32 v237, 0
	v_lshl_add_u64 v[208:209], v[200:201], 0, s[94:95]
	s_mov_b32 s27, 0
	v_add_u32_e32 v234, 8, v96
	v_cmp_ge_u32_e64 s[94:95], v3, v2
	v_add3_u32 v236, s12, v0, v233
	s_sub_i32 s23, s13, s6
	v_mov_b32_e32 v254, 0xff61b1e6
	v_mov_b32_e32 v238, 0xf149f2ca
	s_and_b64 s[0:1], s[0:1], s[38:39]
	s_and_b64 s[40:41], s[40:41], s[42:43]
	s_and_b64 s[44:45], s[44:45], s[46:47]
	s_and_b64 s[48:49], s[48:49], s[50:51]
	s_and_b64 s[52:53], s[52:53], s[54:55]
	s_and_b64 s[56:57], s[56:57], s[58:59]
	s_and_b64 s[60:61], s[60:61], s[62:63]
	s_and_b64 s[64:65], s[64:65], s[66:67]
	s_and_b64 s[68:69], s[68:69], s[70:71]
	s_and_b64 s[72:73], s[72:73], s[74:75]
	s_and_b64 s[76:77], s[76:77], s[78:79]
	s_and_b64 s[82:83], s[82:83], s[84:85]
	s_and_b64 s[86:87], s[86:87], s[88:89]
	s_and_b64 s[90:91], s[90:91], s[92:93]
	s_and_b64 s[94:95], s[94:95], s[96:97]
	s_and_b64 s[98:99], s[98:99], s[4:5]
	v_mov_b32_e32 v48, 0
	v_mov_b32_e32 v49, v237
	v_mov_b32_e32 v50, v237
	v_mov_b32_e32 v51, v237
	v_mov_b32_e32 v52, v237
	v_mov_b32_e32 v53, v237
	v_mov_b32_e32 v54, v237
	v_mov_b32_e32 v55, v237
	v_mov_b32_e32 v56, v237
	v_mov_b32_e32 v57, v237
	v_mov_b32_e32 v58, v237
	v_mov_b32_e32 v59, v237
	v_mov_b32_e32 v60, v237
	v_mov_b32_e32 v61, v237
	v_mov_b32_e32 v62, v237
	v_mov_b32_e32 v63, v237
	v_mov_b32_e32 v32, 0
	v_mov_b32_e32 v33, v237
	v_mov_b32_e32 v34, v237
	v_mov_b32_e32 v35, v237
	v_mov_b32_e32 v36, v237
	v_mov_b32_e32 v37, v237
	v_mov_b32_e32 v38, v237
	v_mov_b32_e32 v39, v237
	v_mov_b32_e32 v40, v237
	v_mov_b32_e32 v41, v237
	v_mov_b32_e32 v42, v237
	v_mov_b32_e32 v43, v237
	v_mov_b32_e32 v44, v237
	v_mov_b32_e32 v45, v237
	v_mov_b32_e32 v46, v237
	v_mov_b32_e32 v47, v237
	v_mov_b32_e32 v16, 0
	v_mov_b32_e32 v17, v237
	v_mov_b32_e32 v18, v237
	v_mov_b32_e32 v19, v237
	v_mov_b32_e32 v20, v237
	v_mov_b32_e32 v21, v237
	v_mov_b32_e32 v22, v237
	v_mov_b32_e32 v23, v237
	v_mov_b32_e32 v24, v237
	v_mov_b32_e32 v25, v237
	v_mov_b32_e32 v26, v237
	v_mov_b32_e32 v27, v237
	v_mov_b32_e32 v28, v237
	v_mov_b32_e32 v29, v237
	v_mov_b32_e32 v30, v237
	v_mov_b32_e32 v31, v237
	v_mov_b32_e32 v0, 0
	v_mov_b32_e32 v1, v237
	v_mov_b32_e32 v2, v237
	v_mov_b32_e32 v3, v237
	v_mov_b32_e32 v4, v237
	v_mov_b32_e32 v5, v237
	v_mov_b32_e32 v6, v237
	v_mov_b32_e32 v7, v237
	v_mov_b32_e32 v8, v237
	v_mov_b32_e32 v9, v237
	v_mov_b32_e32 v10, v237
	v_mov_b32_e32 v11, v237
	v_mov_b32_e32 v12, v237
	v_mov_b32_e32 v13, v237
	v_mov_b32_e32 v14, v237
	v_mov_b32_e32 v15, v237
	s_barrier

; __device__ __forceinline__ void attn_phase(const Args& a, int layer, LAS unsigned char* lds, int G, int need_ctx) {
;     ...
;             if (isl) {
;                 const int kr = r0a + st; const bool rowok = (kr >= myr0) && (kr < myr0 + 8);
;                 const int brow = (kr - qr + 7) * 31 - qcol + 15;
; #pragma unroll
;                 for (int t = 0; t < 16; ++t) {
;                     const int kc = cw + 16 * (t >> 3) + 8 * hh + (t & 7); const bool valid = rowok && (kc >= c0) && (kc < c0 + 16);
;                     const float bias = rp[valid ? (brow + kc) : 0];
;                     sc[t] = valid ? sc[t] + bias : -3.0e38f;
;                 }
;             }
.LBB0_162:
	s_andn2_b64 vcc, exec, s[6:7]
	s_cbranch_vccnz .LBB0_196
	s_add_i32 s12, s37, s27
	v_cmp_ge_u32_e64 s[6:7], s12, v96
	v_cmp_lt_u32_e32 vcc, s12, v234
	s_and_b64 s[6:7], s[6:7], vcc
	v_cndmask_b32_e64 v253, v232, v236, s[6:7]
	ds_read2_b32 v[80:81], v253 offset0:0 offset1:1
	ds_read2_b32 v[82:83], v253 offset0:2 offset1:3
	ds_read2_b32 v[84:85], v253 offset0:4 offset1:5
	ds_read2_b32 v[86:87], v253 offset0:6 offset1:7
	ds_read2_b32 v[88:89], v253 offset0:16 offset1:17
	ds_read2_b32 v[90:91], v253 offset0:18 offset1:19
	ds_read2_b32 v[92:93], v253 offset0:20 offset1:21
	ds_read2_b32 v[94:95], v253 offset0:22 offset1:23
	s_and_b64 vcc, s[6:7], s[0:1]
	s_waitcnt lgkmcnt(7)
	v_add_f32_e32 v80, v64, v80
	v_cndmask_b32_e32 v64, v254, v80, vcc
	s_and_b64 s[12:13], s[6:7], s[40:41]
	v_add_f32_e32 v81, v65, v81
	v_cndmask_b32_e64 v65, v254, v81, s[12:13]
	s_and_b64 vcc, s[6:7], s[44:45]
	s_waitcnt lgkmcnt(6)
	v_add_f32_e32 v82, v66, v82
	v_cndmask_b32_e32 v66, v254, v82, vcc
	s_and_b64 s[12:13], s[6:7], s[48:49]
	v_add_f32_e32 v83, v67, v83
	v_cndmask_b32_e64 v67, v254, v83, s[12:13]
	s_and_b64 vcc, s[6:7], s[52:53]
	s_waitcnt lgkmcnt(5)
	v_add_f32_e32 v84, v68, v84
	v_cndmask_b32_e32 v68, v254, v84, vcc
	s_and_b64 s[12:13], s[6:7], s[56:57]
	v_add_f32_e32 v85, v69, v85
	v_cndmask_b32_e64 v69, v254, v85, s[12:13]
	s_and_b64 vcc, s[6:7], s[60:61]
	s_waitcnt lgkmcnt(4)
	v_add_f32_e32 v86, v70, v86
	v_cndmask_b32_e32 v70, v254, v86, vcc
	s_and_b64 s[12:13], s[6:7], s[64:65]
	v_add_f32_e32 v87, v71, v87
	v_cndmask_b32_e64 v71, v254, v87, s[12:13]
	s_and_b64 vcc, s[6:7], s[68:69]
	s_waitcnt lgkmcnt(3)
	v_add_f32_e32 v88, v72, v88
	v_cndmask_b32_e32 v72, v254, v88, vcc
	s_and_b64 s[12:13], s[6:7], s[72:73]
	v_add_f32_e32 v89, v73, v89
	v_cndmask_b32_e64 v73, v254, v89, s[12:13]
	s_and_b64 vcc, s[6:7], s[76:77]
	s_waitcnt lgkmcnt(2)
	v_add_f32_e32 v90, v74, v90
	v_cndmask_b32_e32 v74, v254, v90, vcc
	s_and_b64 s[12:13], s[6:7], s[82:83]
	v_add_f32_e32 v91, v75, v91
	v_cndmask_b32_e64 v75, v254, v91, s[12:13]
	s_and_b64 vcc, s[6:7], s[86:87]
	s_waitcnt lgkmcnt(1)
	v_add_f32_e32 v92, v76, v92
	v_cndmask_b32_e32 v76, v254, v92, vcc
	s_and_b64 s[12:13], s[6:7], s[90:91]
	v_add_f32_e32 v93, v77, v93
	v_cndmask_b32_e64 v77, v254, v93, s[12:13]
	s_and_b64 vcc, s[6:7], s[94:95]
	s_waitcnt lgkmcnt(0)
	v_add_f32_e32 v94, v78, v94
	v_cndmask_b32_e32 v78, v254, v94, vcc
	s_and_b64 s[12:13], s[6:7], s[98:99]
	v_add_f32_e32 v95, v79, v95
	v_cndmask_b32_e64 v79, v254, v95, s[12:13]

; __device__ __forceinline__ void row_phase(const Args& a, int li, LAS unsigned char* lds, int G, int tid, int wave, int lane) {
;     ...
;                 const bf16_t* yrow = Y + (size_t)row * DM;
;                 u32x2 yw[8];
; #pragma unroll
;                 for (int j = 0; j < 8; ++j) xv[j] = *(const f32x4*)(xrow + 4 * lane + 256 * j);
; #pragma unroll
;                 for (int j = 0; j < 8; ++j) yw[j] = *(const u32x2*)(yrow + 4 * lane + 256 * j);
.Lrow_noy1a:
	global_load_dwordx4 v[8:11], v96, s[24:25]
	s_nop 0
	global_load_dwordx4 v[0:3], v96, s[24:25] offset:1024
	global_load_dwordx4 v[160:163], v96, s[24:25] offset:2048
	global_load_dwordx4 v[164:167], v96, s[24:25] offset:3072
	s_add_u32 s100, s24, 0x1000
	s_addc_u32 s101, s25, 0
	global_load_dwordx4 v[168:171], v96, s[100:101]
	global_load_dwordx4 v[172:175], v96, s[100:101] offset:1024
	global_load_dwordx4 v[176:179], v96, s[100:101] offset:2048
	global_load_dwordx4 v[180:183], v96, s[100:101] offset:3072
	v_cmp_lt_i32_e32 vcc, v211, v212
	s_waitcnt vmcnt(0)
	v_readlane_b32 s100, v251, 50
	s_cmp_eq_u32 s100, 19
	s_cbranch_scc1 .Lrow_noy1b
	v_lshlrev_b32_e32 v150, 16, v4
	v_and_b32_e32 v151, 0xffff0000, v4
	v_lshlrev_b32_e32 v152, 16, v132
	v_and_b32_e32 v153, 0xffff0000, v132
	v_pk_add_f32 v[150:151], v[150:151], v[152:153]
	s_nop 0
	v_cvt_pk_bf16_f32 v4, v150, v151
	v_lshlrev_b32_e32 v154, 16, v5
	v_and_b32_e32 v155, 0xffff0000, v5
	v_lshlrev_b32_e32 v156, 16, v133
	v_and_b32_e32 v157, 0xffff0000, v133
	v_pk_add_f32 v[154:155], v[154:155], v[156:157]
	s_nop 0
	v_cvt_pk_bf16_f32 v5, v154, v155
	v_lshlrev_b32_e32 v150, 16, v6
	v_and_b32_e32 v151, 0xffff0000, v6
	v_lshlrev_b32_e32 v152, 16, v134
	v_and_b32_e32 v153, 0xffff0000, v134
	v_pk_add_f32 v[150:151], v[150:151], v[152:153]
	s_nop 0
	v_cvt_pk_bf16_f32 v6, v150, v151
	v_lshlrev_b32_e32 v154, 16, v7
	v_and_b32_e32 v155, 0xffff0000, v7
	v_lshlrev_b32_e32 v156, 16, v135
	v_and_b32_e32 v157, 0xffff0000, v135
	v_pk_add_f32 v[154:155], v[154:155], v[156:157]
	s_nop 0
	v_cvt_pk_bf16_f32 v7, v154, v155
	v_lshlrev_b32_e32 v150, 16, v12
	v_and_b32_e32 v151, 0xffff0000, v12
	v_lshlrev_b32_e32 v152, 16, v136
	v_and_b32_e32 v153, 0xffff0000, v136
	v_pk_add_f32 v[150:151], v[150:151], v[152:153]
	s_nop 0
	v_cvt_pk_bf16_f32 v12, v150, v151
	v_lshlrev_b32_e32 v154, 16, v13
	v_and_b32_e32 v155, 0xffff0000, v13
	v_lshlrev_b32_e32 v156, 16, v137
	v_and_b32_e32 v157, 0xffff0000, v137
	v_pk_add_f32 v[154:155], v[154:155], v[156:157]
	s_nop 0
	v_cvt_pk_bf16_f32 v13, v154, v155
	v_lshlrev_b32_e32 v150, 16, v14
	v_and_b32_e32 v151, 0xffff0000, v14
	v_lshlrev_b32_e32 v152, 16, v138
	v_and_b32_e32 v153, 0xffff0000, v138
	v_pk_add_f32 v[150:151], v[150:151], v[152:153]
	s_nop 0
	v_cvt_pk_bf16_f32 v14, v150, v151
	v_lshlrev_b32_e32 v154, 16, v15
	v_and_b32_e32 v155, 0xffff0000, v15
	v_lshlrev_b32_e32 v156, 16, v139
	v_and_b32_e32 v157, 0xffff0000, v139
	v_pk_add_f32 v[154:155], v[154:155], v[156:157]
	s_nop 0
	v_cvt_pk_bf16_f32 v15, v154, v155
	v_lshlrev_b32_e32 v150, 16, v16
	v_and_b32_e32 v151, 0xffff0000, v16
	v_lshlrev_b32_e32 v152, 16, v140
	v_and_b32_e32 v153, 0xffff0000, v140
	v_pk_add_f32 v[150:151], v[150:151], v[152:153]
	s_nop 0
	v_cvt_pk_bf16_f32 v16, v150, v151
	v_lshlrev_b32_e32 v154, 16, v17
	v_and_b32_e32 v155, 0xffff0000, v17
	v_lshlrev_b32_e32 v156, 16, v141
	v_and_b32_e32 v157, 0xffff0000, v141
	v_pk_add_f32 v[154:155], v[154:155], v[156:157]
	s_nop 0
	v_cvt_pk_bf16_f32 v17, v154, v155
	v_lshlrev_b32_e32 v150, 16, v18
	v_and_b32_e32 v151, 0xffff0000, v18
	v_lshlrev_b32_e32 v152, 16, v142
	v_and_b32_e32 v153, 0xffff0000, v142
	v_pk_add_f32 v[150:151], v[150:151], v[152:153]
	s_nop 0
	v_cvt_pk_bf16_f32 v18, v150, v151
	v_lshlrev_b32_e32 v154, 16, v19
	v_and_b32_e32 v155, 0xffff0000, v19
	v_lshlrev_b32_e32 v156, 16, v143
	v_and_b32_e32 v157, 0xffff0000, v143
	v_pk_add_f32 v[154:155], v[154:155], v[156:157]
	s_nop 0
	v_cvt_pk_bf16_f32 v19, v154, v155
	v_lshlrev_b32_e32 v150, 16, v20
	v_and_b32_e32 v151, 0xffff0000, v20
	v_lshlrev_b32_e32 v152, 16, v144
	v_and_b32_e32 v153, 0xffff0000, v144
	v_pk_add_f32 v[150:151], v[150:151], v[152:153]
	s_nop 0
	v_cvt_pk_bf16_f32 v20, v150, v151
	v_lshlrev_b32_e32 v154, 16, v21
	v_and_b32_e32 v155, 0xffff0000, v21
	v_lshlrev_b32_e32 v156, 16, v145
	v_and_b32_e32 v157, 0xffff0000, v145
	v_pk_add_f32 v[154:155], v[154:155], v[156:157]
	s_nop 0
	v_cvt_pk_bf16_f32 v21, v154, v155
	v_lshlrev_b32_e32 v150, 16, v22
	v_and_b32_e32 v151, 0xffff0000, v22
	v_lshlrev_b32_e32 v152, 16, v146
	v_and_b32_e32 v153, 0xffff0000, v146
	v_pk_add_f32 v[150:151], v[150:151], v[152:153]
	s_nop 0
	v_cvt_pk_bf16_f32 v22, v150, v151
	v_lshlrev_b32_e32 v154, 16, v23
	v_and_b32_e32 v155, 0xffff0000, v23
	v_lshlrev_b32_e32 v156, 16, v147
	v_and_b32_e32 v157, 0xffff0000, v147
	v_pk_add_f32 v[154:155], v[154:155], v[156:157]
	s_nop 0
	v_cvt_pk_bf16_f32 v23, v154, v155
; __device__ __forceinline__ float bflo(unsigned w) { return __uint_as_float(w << 16); }
; __device__ __forceinline__ float bfhi(unsigned w) { return __uint_as_float(w & 0xffff0000u); }
; __device__ __forceinline__ void row_phase(const Args& a, int li, LAS unsigned char* lds, int G, int tid, int wave, int lane) {
;     ...
;                 f32x4 yv[8]; float ss = 0.f;
; #pragma unroll
;                 for (int j = 0; j < 8; ++j) { yv[j] = (f32x4){bflo(yw[j].x), bfhi(yw[j].x), bflo(yw[j].y), bfhi(yw[j].y)}; ss += (yv[j].x * yv[j].x + yv[j].y * yv[j].y) + (yv[j].z * yv[j].z + yv[j].w * yv[j].w); }
;                 const float rstd = rsqrtf(wave_sum(ss) * (1.0f / DM) + EPS);
.Lrow_noy1b:
	v_and_b32_e32 v79, 0xffff0000, v4
	v_and_b32_e32 v81, 0xffff0000, v5
	v_lshlrev_b32_e32 v78, 16, v4
	s_waitcnt vmcnt(6)
	v_lshlrev_b32_e32 v55, 16, v14
	v_lshlrev_b32_e32 v80, 16, v5
	v_lshlrev_b32_e32 v83, 16, v7
	v_lshlrev_b32_e32 v82, 16, v6
	v_and_b32_e32 v85, 0xffff0000, v7
	v_and_b32_e32 v84, 0xffff0000, v6
	v_lshlrev_b32_e32 v86, 16, v12
	v_and_b32_e32 v87, 0xffff0000, v12
	v_lshlrev_b32_e32 v88, 16, v13
	v_and_b32_e32 v89, 0xffff0000, v13
	v_and_b32_e32 v31, 0xffff0000, v14
	v_lshlrev_b32_e32 v28, 16, v15
	v_and_b32_e32 v29, 0xffff0000, v15
	s_waitcnt vmcnt(4)
	v_lshlrev_b32_e32 v13, 16, v19
	v_lshlrev_b32_e32 v12, 16, v18
	v_and_b32_e32 v15, 0xffff0000, v19
	v_and_b32_e32 v14, 0xffff0000, v18
	s_waitcnt vmcnt(2)
	v_and_b32_e32 v7, 0xffff0000, v22
	v_mul_f32_e32 v6, v81, v81
	v_mul_f32_e32 v18, v79, v79
	v_mov_b32_e32 v19, v55
	v_lshlrev_b32_e32 v91, 16, v17
	v_lshlrev_b32_e32 v90, 16, v16
	v_and_b32_e32 v93, 0xffff0000, v17
	v_and_b32_e32 v92, 0xffff0000, v16
	v_lshlrev_b32_e32 v53, 16, v22
	v_pk_mul_f32 v[16:17], v[84:85], v[84:85]
	v_pk_fma_f32 v[62:63], v[80:81], v[80:81], v[6:7] op_sel_hi:[1,1,0]
	v_pk_fma_f32 v[64:65], v[78:79], v[78:79], v[18:19] op_sel_hi:[1,1,0]
	v_lshlrev_b32_e32 v24, 16, v20
	v_and_b32_e32 v25, 0xffff0000, v20
	v_lshlrev_b32_e32 v26, 16, v21
	v_and_b32_e32 v27, 0xffff0000, v21
	v_mul_f32_e32 v20, v87, v87
	v_mul_f32_e32 v22, v89, v89
	v_mov_b32_e32 v21, v53
	v_pk_fma_f32 v[16:17], v[82:83], v[82:83], v[16:17]
	v_mov_b32_e32 v54, v64
	v_mov_b32_e32 v18, v62
	v_lshlrev_b32_e32 v4, 16, v23
	v_and_b32_e32 v5, 0xffff0000, v23
	v_mul_f32_e32 v72, v31, v31
	v_mul_f32_e32 v73, v28, v28
	v_mul_f32_e32 v74, v29, v29
	v_pk_fma_f32 v[66:67], v[86:87], v[86:87], v[20:21] op_sel_hi:[1,1,0]
	v_pk_fma_f32 v[22:23], v[88:89], v[88:89], v[22:23] op_sel_hi:[1,1,0]
	v_pk_add_f32 v[62:63], v[64:65], v[62:63]
	v_pk_add_f32 v[16:17], v[16:17], v[16:17] op_sel:[0,1] op_sel_hi:[1,0]
	v_pk_mul_f32 v[18:19], v[54:55], v[18:19]
	v_mov_b32_e32 v67, v73
	v_mov_b32_e32 v23, v74
	v_mov_b32_e32 v17, v72
	v_mov_b32_e32 v63, v19
	v_pk_mul_f32 v[58:59], v[92:93], v[92:93]
	v_pk_add_f32 v[22:23], v[66:67], v[22:23]
	v_pk_add_f32 v[16:17], v[62:63], v[16:17]
	v_pk_fma_f32 v[58:59], v[90:91], v[90:91], v[58:59]
	v_pk_add_f32 v[16:17], v[16:17], v[22:23]
	v_pk_mul_f32 v[60:61], v[14:15], v[14:15]
	v_mul_f32_e32 v52, v27, v27
	v_pk_add_f32 v[58:59], v[58:59], v[58:59] op_sel:[0,1] op_sel_hi:[1,0]
	v_pk_add_f32 v[16:17], v[16:17], v[16:17] op_sel:[0,1] op_sel_hi:[1,0]
	v_mul_f32_e32 v30, v25, v25
	v_pk_fma_f32 v[60:61], v[12:13], v[12:13], v[60:61]
	v_pk_fma_f32 v[70:71], v[26:27], v[26:27], v[52:53] op_sel_hi:[1,1,0]
	v_mov_b32_e32 v20, v58
	v_mov_b32_e32 v52, v16
	v_mul_f32_e32 v75, v7, v7
	v_mul_f32_e32 v76, v4, v4
	v_mul_f32_e32 v77, v5, v5
	v_pk_fma_f32 v[68:69], v[24:25], v[24:25], v[30:31] op_sel_hi:[1,1,0]
	v_pk_add_f32 v[60:61], v[60:61], v[60:61] op_sel:[0,1] op_sel_hi:[1,0]
	v_pk_add_f32 v[16:17], v[16:17], v[58:59]
	v_pk_mul_f32 v[18:19], v[52:53], v[20:21]
	v_mov_b32_e32 v69, v76
	v_mov_b32_e32 v71, v77
	v_mov_b32_e32 v61, v75
	v_mov_b32_e32 v17, v19
	v_pk_add_f32 v[64:65], v[68:69], v[70:71]
	v_pk_add_f32 v[16:17], v[16:17], v[60:61]
	v_lshl_add_u64 v[20:21], s[24:25], 0, v[96:97]
	v_pk_add_f32 v[16:17], v[16:17], v[64:65]
	v_mov_b32_e32 v54, v90
	v_add_f32_e32 v6, v16, v17
	v_cndmask_b32_e32 v16, v210, v211, vcc
	v_lshlrev_b32_e32 v16, 2, v16
	ds_bpermute_b32 v22, v16, v6
	v_cmp_lt_i32_e32 vcc, v213, v212
	s_waitcnt lgkmcnt(0)
	v_add_f32_e32 v6, v6, v22
	v_cndmask_b32_e32 v22, v210, v213, vcc
	v_add_co_u32_e32 v94, vcc, 0x1000, v20
	v_lshlrev_b32_e32 v22, 2, v22
	s_nop 0
	v_addc_co_u32_e32 v95, vcc, 0, v21, vcc
	ds_bpermute_b32 v22, v22, v6
	v_cmp_lt_i32_e32 vcc, v214, v212
	s_waitcnt lgkmcnt(0)
	v_add_f32_e32 v6, v6, v22
	v_cndmask_b32_e32 v20, v210, v214, vcc
	v_lshlrev_b32_e32 v20, 2, v20
	ds_bpermute_b32 v20, v20, v6
	v_cmp_lt_i32_e32 vcc, v215, v212
	s_waitcnt lgkmcnt(0)
; __device__ __forceinline__ void row_phase(const Args& a, int li, LAS unsigned char* lds, int G, int tid, int wave, int lane) {
;     ...
;                 const float rstd = rsqrtf(wave_sum(ss) * (1.0f / DM) + EPS);
; #pragma unroll
;                 for (int j = 0; j < 8; ++j) {
;                     xv[j] += Vr[0 * 512 + 64 * j] * (yv[j] * rstd);
;                     *(f32x4*)(xrow + 4 * lane + 256 * j) = xv[j];
;                 }
	v_add_f32_e32 v6, v6, v20
	v_cndmask_b32_e32 v20, v210, v215, vcc
	v_lshlrev_b32_e32 v20, 2, v20
	ds_bpermute_b32 v20, v20, v6
	s_waitcnt lgkmcnt(0)
	v_add_f32_e32 v6, v6, v20
	v_xor_b32_e32 v20, 16, v210
	v_cmp_lt_i32_e32 vcc, v20, v212
	s_nop 1
	v_cndmask_b32_e32 v20, v210, v20, vcc
	v_lshlrev_b32_e32 v20, 2, v20
	ds_bpermute_b32 v20, v20, v6
	s_waitcnt lgkmcnt(0)
	v_add_f32_e32 v6, v6, v20
	v_xor_b32_e32 v20, 32, v210
	v_cmp_lt_i32_e32 vcc, v20, v212
	s_nop 1
	v_cndmask_b32_e32 v20, v210, v20, vcc
	v_lshlrev_b32_e32 v20, 2, v20
	ds_bpermute_b32 v20, v20, v6
	s_waitcnt lgkmcnt(0)
	v_add_f32_e32 v6, v6, v20
	v_fmamk_f32 v6, v6, 0x3a000000, v197
	v_mul_f32_e32 v20, 0x4b800000, v6
	v_cmp_gt_f32_e32 vcc, s21, v6
	s_nop 1
	v_cndmask_b32_e32 v6, v6, v20, vcc
	v_rsq_f32_e32 v6, v6
	ds_read_b128 v[20:23], v57
	v_mul_f32_e32 v30, 0x45800000, v6
	v_cndmask_b32_e32 v52, v6, v30, vcc
	v_pk_mul_f32 v[98:99], v[52:53], v[78:79] op_sel_hi:[0,1]
	v_pk_mul_f32 v[100:101], v[52:53], v[80:81] op_sel_hi:[0,1]
	ds_read_b128 v[78:81], v57 offset:1024
	s_waitcnt vmcnt(7) lgkmcnt(1)
	v_pk_fma_f32 v[20:21], v[20:21], v[98:99], v[8:9]
	v_mov_b32_e32 v8, v82
	v_mov_b32_e32 v9, v84
	v_mov_b32_e32 v84, v83
	v_pk_fma_f32 v[22:23], v[22:23], v[100:101], v[10:11]
	v_pk_mul_f32 v[8:9], v[52:53], v[8:9] op_sel_hi:[0,1]
	v_pk_mul_f32 v[10:11], v[52:53], v[84:85] op_sel_hi:[0,1]
	s_waitcnt vmcnt(6) lgkmcnt(0)
	v_pk_fma_f32 v[10:11], v[80:81], v[10:11], v[2:3]
	v_pk_fma_f32 v[8:9], v[78:79], v[8:9], v[0:1]
	ds_read_b128 v[0:3], v57 offset:2048
	ds_read_b128 v[78:81], v57 offset:3072
	v_pk_mul_f32 v[82:83], v[52:53], v[86:87] op_sel_hi:[0,1]
	v_pk_mul_f32 v[84:85], v[52:53], v[88:89] op_sel_hi:[0,1]
	v_mov_b32_e32 v30, v55
	s_waitcnt vmcnt(5) lgkmcnt(1)
	v_pk_fma_f32 v[18:19], v[2:3], v[84:85], v[162:163]
	v_pk_fma_f32 v[16:17], v[0:1], v[82:83], v[160:161]
	v_pk_mul_f32 v[0:1], v[30:31], v[52:53] op_sel_hi:[1,0]
	v_pk_mul_f32 v[2:3], v[28:29], v[52:53] op_sel_hi:[1,0]
	ds_read_b128 v[28:31], v57 offset:4096
	s_waitcnt vmcnt(4) lgkmcnt(1)
	v_pk_fma_f32 v[2:3], v[80:81], v[2:3], v[166:167]
	v_pk_fma_f32 v[0:1], v[78:79], v[0:1], v[164:165]
	ds_read_b128 v[58:61], v57 offset:5120
	v_mov_b32_e32 v55, v92
	v_pk_mul_f32 v[54:55], v[52:53], v[54:55] op_sel_hi:[0,1]
	v_mov_b32_e32 v92, v91
	s_waitcnt vmcnt(3) lgkmcnt(1)
	v_pk_fma_f32 v[28:29], v[28:29], v[54:55], v[168:169]
	v_mov_b32_e32 v54, v12
	v_mov_b32_e32 v55, v14
	v_mov_b32_e32 v14, v13
	v_pk_mul_f32 v[78:79], v[52:53], v[92:93] op_sel_hi:[0,1]
	v_pk_mul_f32 v[54:55], v[52:53], v[54:55] op_sel_hi:[0,1]
	v_pk_mul_f32 v[12:13], v[52:53], v[14:15] op_sel_hi:[0,1]
	v_pk_fma_f32 v[30:31], v[30:31], v[78:79], v[170:171]
	s_waitcnt vmcnt(2) lgkmcnt(0)
	v_pk_fma_f32 v[14:15], v[60:61], v[12:13], v[174:175]
	v_pk_fma_f32 v[12:13], v[58:59], v[54:55], v[172:173]
	ds_read_b128 v[58:61], v57 offset:6144
	ds_read_b128 v[62:65], v57 offset:7168
	v_mov_b32_e32 v6, v53
	v_pk_mul_f32 v[24:25], v[52:53], v[24:25] op_sel_hi:[0,1]
	v_pk_mul_f32 v[26:27], v[52:53], v[26:27] op_sel_hi:[0,1]
	v_pk_mul_f32 v[54:55], v[6:7], v[52:53] op_sel_hi:[1,0]
	v_pk_mul_f32 v[4:5], v[4:5], v[52:53] op_sel_hi:[1,0]
	s_waitcnt vmcnt(1) lgkmcnt(1)
	v_pk_fma_f32 v[26:27], v[60:61], v[26:27], v[178:179]
	v_pk_fma_f32 v[24:25], v[58:59], v[24:25], v[176:177]
	s_waitcnt vmcnt(0) lgkmcnt(0)
	v_pk_fma_f32 v[6:7], v[64:65], v[4:5], v[182:183]
	v_pk_fma_f32 v[4:5], v[62:63], v[54:55], v[180:181]
	global_store_dwordx4 v96, v[20:23], s[24:25]
	global_store_dwordx4 v96, v[8:11], s[24:25] offset:1024
	global_store_dwordx4 v96, v[16:19], s[24:25] offset:2048
	global_store_dwordx4 v96, v[0:3], s[24:25] offset:3072
	global_store_dwordx4 v[94:95], v[28:31], off
	global_store_dwordx4 v[94:95], v[12:15], off offset:1024
	global_store_dwordx4 v[94:95], v[24:27], off offset:2048
	global_store_dwordx4 v[94:95], v[4:7], off offset:3072
	s_cbranch_execnz .LBB0_214
